# non-temporal (nt) loads for the two streaming reads of x_prompt/x_sample (prologue and layer-0 row pass): keep the Infinity Cache for the phase-to-phase intermediates
# speedup vs baseline: 1.0336x; 1.0336x over previous
.LBB0_46:
	s_andn2_b64 vcc, exec, s[4:5]
	s_cbranch_vccnz .LBB0_48
	s_lshl_b32 s5, s40, 2
	s_add_i32 s4, s5, 0xfffffc00
	s_add_i32 s42, s5, 0xfffffc02
	s_add_i32 s10, s5, 0xfffffc03
	s_add_i32 s6, s5, 0xffff7c03
	s_cmpk_lt_u32 s4, 0x8000
	s_cselect_b32 s44, s10, s6
	s_cselect_b32 s45, 0, 0
	s_add_i32 s6, s5, 0xffff7c02
	s_cmpk_lt_u32 s4, 0x8000
	s_cselect_b32 s7, 0, 8
	s_cselect_b32 s47, 0, 0
	s_cselect_b32 s46, s42, s6
	s_add_i32 s6, s5, 0xfffffc01
	s_add_i32 s43, s5, 0xffff7c01
	s_cmpk_lt_u32 s4, 0x8000
	s_cselect_b32 s48, s6, s43
	s_cselect_b32 s49, 0, 0
	s_add_i32 s5, s5, 0xffff7c00
	s_cmpk_lt_u32 s40, 0x2100
	s_cselect_b32 s56, s4, s5
	s_cselect_b32 s5, 0, 8
	s_cselect_b32 s57, 0, 0
	s_add_u32 s50, s8, s5
	s_addc_u32 s51, s9, 0
	s_load_dwordx2 s[50:51], s[50:51], 0x0
	s_lshl_b64 s[58:59], s[56:57], 12
	v_ashrrev_i32_e32 v89, 31, v88
	s_load_dwordx2 s[60:61], s[8:9], 0xc0
	v_lshlrev_b64 v[34:35], 4, v[88:89]
	s_waitcnt lgkmcnt(0)
	s_add_u32 s50, s50, s58
	s_addc_u32 s51, s51, s59
	v_lshl_add_u64 v[26:27], s[50:51], 0, v[34:35]
	global_load_dwordx4 v[30:33], v[26:27], off nt
	global_load_dwordx4 v[22:25], v[26:27], off offset:1024 nt
	global_load_dwordx4 v[18:21], v[26:27], off offset:3072 nt
	s_nop 0
	global_load_dwordx4 v[26:29], v[26:27], off offset:2048 nt
	v_and_b32_e32 v1, 64, v96
	v_xor_b32_e32 v36, 1, v96
	v_add_u32_e32 v50, 64, v1
	v_xor_b32_e32 v37, 2, v96
	v_cmp_lt_i32_e32 vcc, v36, v50
	v_xor_b32_e32 v38, 4, v96
	v_xor_b32_e32 v39, 8, v96
	v_cndmask_b32_e32 v1, v96, v36, vcc
	v_cmp_lt_i32_e32 vcc, v37, v50
	v_xor_b32_e32 v40, 16, v96
	v_xor_b32_e32 v47, 32, v96
	v_cndmask_b32_e32 v51, v96, v37, vcc
	v_cmp_lt_i32_e32 vcc, v38, v50
	s_add_u32 s50, s8, s7
	s_addc_u32 s51, s9, 0
	v_cndmask_b32_e32 v52, v96, v38, vcc
	v_cmp_lt_i32_e32 vcc, v39, v50
	v_lshlrev_b32_e32 v1, 2, v1
	s_load_dwordx2 s[50:51], s[50:51], 0x0
	v_cndmask_b32_e32 v53, v96, v39, vcc
	v_cmp_lt_i32_e32 vcc, v40, v50
	s_lshl_b64 s[48:49], s[48:49], 12
	v_lshlrev_b32_e32 v93, 2, v51
	v_cndmask_b32_e32 v54, v96, v40, vcc
	s_waitcnt lgkmcnt(0)
	s_add_u32 s48, s50, s48
	s_addc_u32 s49, s51, s49
	v_lshlrev_b32_e32 v82, 2, v54
	v_cmp_lt_i32_e32 vcc, v47, v50
	v_lshlrev_b32_e32 v92, 2, v52
	v_lshlrev_b32_e32 v86, 2, v53
	s_lshl_b64 s[46:47], s[46:47], 12
	s_add_u32 s46, s50, s46
	s_addc_u32 s47, s51, s47
	s_lshl_b64 s[44:45], s[44:45], 12
	s_mov_b32 s5, s11
	s_add_u32 s44, s50, s44
	s_addc_u32 s45, s51, s45
	v_lshl_add_u64 v[102:103], s[44:45], 0, v[34:35]
	s_mov_b32 s7, s11
	s_mov_b32 s43, s11
	s_waitcnt vmcnt(3)
	v_pk_mul_f32 v[36:37], v[32:33], v[32:33]
	v_pk_mul_f32 v[38:39], v[30:31], v[30:31]
	s_waitcnt vmcnt(2)
	v_pk_mul_f32 v[40:41], v[24:25], v[24:25]
	v_pk_mul_f32 v[42:43], v[22:23], v[22:23]
	v_pk_mov_b32 v[48:49], v[38:39], v[36:37] op_sel:[1,0]
	v_mov_b32_e32 v39, v37
	v_pk_mov_b32 v[36:37], v[42:43], v[40:41] op_sel:[1,0]
	v_mov_b32_e32 v43, v41
	s_waitcnt vmcnt(0)
	v_mul_f32_e32 v44, v27, v27
	v_mul_f32_e32 v46, v29, v29
	v_pk_add_f32 v[38:39], v[48:49], v[38:39]
	v_pk_add_f32 v[36:37], v[36:37], v[42:43]
	v_mul_f32_e32 v55, v18, v18
	v_mul_f32_e32 v56, v19, v19
	v_mul_f32_e32 v57, v20, v20
	v_mul_f32_e32 v58, v21, v21
	v_pk_fma_f32 v[40:41], v[26:27], v[26:27], v[44:45] op_sel_hi:[1,1,0]
	v_pk_fma_f32 v[44:45], v[28:29], v[28:29], v[46:47] op_sel_hi:[1,1,0]
	v_pk_add_f32 v[38:39], v[38:39], v[38:39] op_sel:[0,1] op_sel_hi:[1,0]
	v_pk_add_f32 v[36:37], v[36:37], v[36:37] op_sel:[0,1] op_sel_hi:[1,0]
	v_mov_b32_e32 v41, v57
	v_mov_b32_e32 v45, v58
	v_mov_b32_e32 v39, v55
	v_mov_b32_e32 v37, v56
	v_pk_add_f32 v[40:41], v[40:41], v[44:45]
	v_pk_add_f32 v[36:37], v[38:39], v[36:37]
	v_cndmask_b32_e32 v38, v96, v47, vcc
	v_pk_add_f32 v[36:37], v[36:37], v[40:41]
	v_lshlrev_b32_e32 v62, 2, v38
	v_add_f32_e32 v36, v36, v37
	ds_bpermute_b32 v37, v1, v36
	s_waitcnt lgkmcnt(0)
	v_add_f32_e32 v39, v36, v37
	v_lshl_add_u64 v[36:37], v[88:89], 3, s[60:61]
	v_lshl_add_u64 v[90:91], v[36:37], 0, s[26:27]
	v_lshl_add_u64 v[36:37], s[48:49], 0, v[34:35]
	global_load_dwordx4 v[98:101], v[36:37], off nt
	global_load_dwordx4 v[54:57], v[36:37], off offset:1024 nt
	global_load_dwordx4 v[50:53], v[36:37], off offset:3072 nt
	global_load_dwordx4 v[58:61], v[36:37], off offset:2048 nt
	ds_bpermute_b32 v40, v93, v39
	v_lshl_add_u64 v[36:37], s[46:47], 0, v[34:35]
	s_lshl_b64 s[46:47], s[4:5], 11
	s_waitcnt lgkmcnt(0)
	v_add_f32_e32 v38, v39, v40
	ds_bpermute_b32 v39, v92, v38
	s_waitcnt lgkmcnt(0)
	v_add_f32_e32 v38, v38, v39
	ds_bpermute_b32 v39, v86, v38
	s_waitcnt lgkmcnt(0)
	v_add_f32_e32 v38, v38, v39
	ds_bpermute_b32 v39, v82, v38
	s_waitcnt lgkmcnt(0)
	v_add_f32_e32 v38, v38, v39
	ds_bpermute_b32 v39, v62, v38
	s_waitcnt lgkmcnt(0)
	v_add_f32_e32 v38, v38, v39
	v_fmamk_f32 v38, v38, 0x3a800000, v94
	v_mul_f32_e32 v39, 0x4f800000, v38
	v_cmp_gt_f32_e32 vcc, s69, v38
	s_nop 1
	v_cndmask_b32_e32 v38, v38, v39, vcc
	v_sqrt_f32_e32 v39, v38
	s_nop 0
	v_add_u32_e32 v40, -1, v39
	v_add_u32_e32 v41, 1, v39
	v_fma_f32 v42, -v40, v39, v38
	v_fma_f32 v43, -v41, v39, v38
	v_cmp_ge_f32_e64 s[4:5], 0, v42
	s_nop 1
	v_cndmask_b32_e64 v39, v39, v40, s[4:5]
	v_cmp_lt_f32_e64 s[4:5], 0, v43
	s_nop 1
	v_cndmask_b32_e64 v39, v39, v41, s[4:5]
	v_mul_f32_e32 v40, 0x37800000, v39
	v_cndmask_b32_e32 v39, v39, v40, vcc
	v_cmp_class_f32_e32 vcc, v38, v95
	s_nop 1
	v_cndmask_b32_e32 v38, v39, v38, vcc
	v_div_scale_f32 v39, s[4:5], v38, v38, 1.0
	v_rcp_f32_e32 v40, v39
	v_div_scale_f32 v34, vcc, 1.0, v38, 1.0
	v_fma_f32 v35, -v39, v40, 1.0
	v_fmac_f32_e32 v40, v35, v40
	v_mul_f32_e32 v35, v34, v40
	v_fma_f32 v41, -v39, v35, v34
	v_fmac_f32_e32 v35, v41, v40
	v_fma_f32 v34, -v39, v35, v34
	v_div_fmas_f32 v34, v34, v40, v35
	v_div_fixup_f32 v34, v34, v38, 1.0
	v_pk_mul_f32 v[30:31], v[30:31], v[34:35] op_sel_hi:[1,0]
	v_pk_mul_f32 v[32:33], v[32:33], v[34:35] op_sel_hi:[1,0]
	v_pk_mul_f32 v[112:113], v[18:19], v[34:35] op_sel_hi:[1,0]
	v_pk_mul_f32 v[114:115], v[20:21], v[34:35] op_sel_hi:[1,0]
	v_pk_mul_f32 v[18:19], v[4:5], v[32:33]
	v_pk_mul_f32 v[20:21], v[2:3], v[30:31]
	v_pk_mul_f32 v[104:105], v[22:23], v[34:35] op_sel_hi:[1,0]
	v_pk_mul_f32 v[106:107], v[24:25], v[34:35] op_sel_hi:[1,0]
	v_bfe_u32 v22, v20, 16, 1
	v_bfe_u32 v24, v18, 16, 1
	v_bfe_u32 v23, v21, 16, 1
	v_bfe_u32 v25, v19, 16, 1
	v_add3_u32 v20, v20, v22, s64
	v_add3_u32 v18, v18, v24, s64
	v_pk_mul_f32 v[104:105], v[6:7], v[104:105]
	v_add3_u32 v21, v21, v23, s64
	v_add3_u32 v19, v19, v25, s64
	v_lshrrev_b32_e32 v20, 16, v20
	v_lshrrev_b32_e32 v18, 16, v18
	v_bfe_u32 v89, v104, 16, 1
	v_pk_mul_f32 v[108:109], v[26:27], v[34:35] op_sel_hi:[1,0]
	v_pk_mul_f32 v[110:111], v[28:29], v[34:35] op_sel_hi:[1,0]
	v_and_or_b32 v116, v21, s66, v20
	v_and_or_b32 v117, v19, s66, v18
	global_load_dwordx4 v[46:49], v[36:37], off nt
	global_load_dwordx4 v[42:45], v[36:37], off offset:1024 nt
	global_load_dwordx4 v[38:41], v[36:37], off offset:2048 nt
	s_nop 0
	global_load_dwordx4 v[34:37], v[36:37], off offset:3072 nt
	s_nop 0
	global_load_dwordx4 v[30:33], v[102:103], off nt
	global_load_dwordx4 v[26:29], v[102:103], off offset:1024 nt
	global_load_dwordx4 v[22:25], v[102:103], off offset:2048 nt
	global_load_dwordx4 v[18:21], v[102:103], off offset:3072 nt
	v_lshl_add_u64 v[102:103], v[90:91], 0, s[46:47]
	v_add3_u32 v89, v104, v89, s64
	v_bfe_u32 v104, v105, 16, 1
	global_store_dwordx2 v[102:103], v[116:117], off sc1
	v_add3_u32 v116, v105, v104, s64
	v_pk_mul_f32 v[104:105], v[8:9], v[106:107]
	v_lshrrev_b32_e32 v89, 16, v89
	v_bfe_u32 v106, v104, 16, 1
	v_add3_u32 v106, v104, v106, s64
	v_bfe_u32 v104, v105, 16, 1
	v_add3_u32 v105, v105, v104, s64
	v_and_or_b32 v104, v116, s66, v89
	v_lshrrev_b32_e32 v89, 16, v106
	v_and_or_b32 v105, v105, s66, v89
	global_store_dwordx2 v[102:103], v[104:105], off offset:512 sc1
	s_waitcnt vmcnt(13)
	v_pk_mul_f32 v[104:105], v[100:101], v[100:101]
	v_pk_mul_f32 v[106:107], v[98:99], v[98:99]
	s_nop 0
	v_pk_mov_b32 v[116:117], v[106:107], v[104:105] op_sel:[1,0]
	v_mov_b32_e32 v107, v105
	v_pk_add_f32 v[104:105], v[116:117], v[106:107]
	s_waitcnt vmcnt(12)
	v_pk_mul_f32 v[106:107], v[56:57], v[56:57]
	v_pk_mul_f32 v[116:117], v[54:55], v[54:55]
	v_pk_add_f32 v[104:105], v[104:105], v[104:105] op_sel:[0,1] op_sel_hi:[1,0]
	v_pk_mov_b32 v[118:119], v[116:117], v[106:107] op_sel:[1,0]
	v_mov_b32_e32 v117, v107
	v_pk_add_f32 v[106:107], v[118:119], v[116:117]
	s_waitcnt vmcnt(11)
	v_mul_f32_e32 v105, v50, v50
	v_pk_add_f32 v[106:107], v[106:107], v[106:107] op_sel:[0,1] op_sel_hi:[1,0]
	s_waitcnt vmcnt(10)
	v_mul_f32_e32 v116, v61, v61
	v_mul_f32_e32 v107, v51, v51
	v_pk_add_f32 v[104:105], v[104:105], v[106:107]
	v_mul_f32_e32 v106, v59, v59
	v_pk_fma_f32 v[106:107], v[58:59], v[58:59], v[106:107] op_sel_hi:[1,1,0]
	v_pk_fma_f32 v[116:117], v[60:61], v[60:61], v[116:117] op_sel_hi:[1,1,0]
	v_mul_f32_e32 v107, v52, v52
	v_mul_f32_e32 v117, v53, v53
	v_pk_add_f32 v[106:107], v[106:107], v[116:117]
	s_nop 0
	v_pk_add_f32 v[104:105], v[104:105], v[106:107]
	s_nop 0
	v_add_f32_e32 v89, v104, v105
	ds_bpermute_b32 v106, v1, v89
	v_pk_mul_f32 v[104:105], v[10:11], v[108:109]
	s_waitcnt lgkmcnt(0)
	v_add_f32_e32 v89, v89, v106
	ds_bpermute_b32 v106, v93, v89
	v_bfe_u32 v107, v104, 16, 1
	v_add3_u32 v107, v104, v107, s64
	v_bfe_u32 v104, v105, 16, 1
	v_add3_u32 v108, v105, v104, s64
	s_waitcnt lgkmcnt(0)
	v_add_f32_e32 v89, v89, v106
	ds_bpermute_b32 v106, v92, v89
	v_pk_mul_f32 v[104:105], v[12:13], v[110:111]
	s_waitcnt lgkmcnt(0)
	v_add_f32_e32 v89, v89, v106
	ds_bpermute_b32 v106, v86, v89
	v_bfe_u32 v109, v104, 16, 1
	v_add3_u32 v109, v104, v109, s64
	v_bfe_u32 v104, v105, 16, 1
	v_add3_u32 v105, v105, v104, s64
	s_waitcnt lgkmcnt(0)
	v_add_f32_e32 v89, v89, v106
	ds_bpermute_b32 v106, v82, v89
	v_lshrrev_b32_e32 v104, 16, v107
	v_lshrrev_b32_e32 v107, 16, v109
	v_and_or_b32 v104, v108, s66, v104
	v_and_or_b32 v105, v105, s66, v107
	s_waitcnt lgkmcnt(0)
	v_add_f32_e32 v89, v89, v106
	ds_bpermute_b32 v106, v62, v89
	global_store_dwordx2 v[102:103], v[104:105], off offset:1024 sc1
	v_pk_mul_f32 v[104:105], v[14:15], v[112:113]
	s_waitcnt lgkmcnt(0)
	v_add_f32_e32 v89, v89, v106
	v_fmamk_f32 v89, v89, 0x3a800000, v94
	v_mul_f32_e32 v106, 0x4f800000, v89
	v_cmp_gt_f32_e32 vcc, s69, v89
	v_bfe_u32 v107, v104, 16, 1
	v_add3_u32 v107, v104, v107, s64
	v_cndmask_b32_e32 v89, v89, v106, vcc
	v_bfe_u32 v104, v105, 16, 1
	v_sqrt_f32_e32 v106, v89
	v_add3_u32 v108, v105, v104, s64
	v_pk_mul_f32 v[104:105], v[16:17], v[114:115]
	s_nop 0
	v_bfe_u32 v109, v104, 16, 1
	v_add3_u32 v109, v104, v109, s64
	v_bfe_u32 v104, v105, 16, 1
	v_add3_u32 v105, v105, v104, s64
	v_lshrrev_b32_e32 v104, 16, v107
	v_add_u32_e32 v107, -1, v106
	v_and_or_b32 v104, v108, s66, v104
	v_fma_f32 v108, -v107, v106, v89
	v_cmp_ge_f32_e64 s[4:5], 0, v108
	v_add_u32_e32 v108, 1, v106
	s_nop 0
	v_cndmask_b32_e64 v107, v106, v107, s[4:5]
	v_fma_f32 v106, -v108, v106, v89
	v_cmp_lt_f32_e64 s[4:5], 0, v106
	s_nop 1
	v_cndmask_b32_e64 v106, v107, v108, s[4:5]
	v_mul_f32_e32 v107, 0x37800000, v106
	v_cndmask_b32_e32 v106, v106, v107, vcc
	v_cmp_class_f32_e32 vcc, v89, v95
	v_lshrrev_b32_e32 v108, 16, v109
	v_and_or_b32 v105, v105, s66, v108
	v_cndmask_b32_e32 v89, v106, v89, vcc
	v_div_scale_f32 v106, s[4:5], v89, v89, 1.0
	v_rcp_f32_e32 v107, v106
	global_store_dwordx2 v[102:103], v[104:105], off offset:1536 sc1
	s_lshl_b64 s[4:5], s[6:7], 11
	v_fma_f32 v102, -v106, v107, 1.0
	v_fmac_f32_e32 v107, v102, v107
	v_div_scale_f32 v102, vcc, 1.0, v89, 1.0
	v_mul_f32_e32 v103, v102, v107
	v_fma_f32 v104, -v106, v103, v102
	v_fmac_f32_e32 v103, v104, v107
	v_fma_f32 v102, -v106, v103, v102
	v_div_fmas_f32 v102, v102, v107, v103
	v_div_fixup_f32 v102, v102, v89, 1.0
	v_pk_mul_f32 v[98:99], v[98:99], v[102:103] op_sel_hi:[1,0]
	v_pk_mul_f32 v[100:101], v[100:101], v[102:103] op_sel_hi:[1,0]
	v_pk_mul_f32 v[98:99], v[2:3], v[98:99]
	v_pk_mul_f32 v[54:55], v[54:55], v[102:103] op_sel_hi:[1,0]
	v_bfe_u32 v89, v98, 16, 1
	v_add3_u32 v89, v98, v89, s64
	v_bfe_u32 v98, v99, 16, 1
	v_pk_mul_f32 v[56:57], v[56:57], v[102:103] op_sel_hi:[1,0]
	v_pk_mul_f32 v[58:59], v[58:59], v[102:103] op_sel_hi:[1,0]
	v_pk_mul_f32 v[60:61], v[60:61], v[102:103] op_sel_hi:[1,0]
	v_pk_mul_f32 v[50:51], v[50:51], v[102:103] op_sel_hi:[1,0]
	v_pk_mul_f32 v[52:53], v[52:53], v[102:103] op_sel_hi:[1,0]
	v_add3_u32 v102, v99, v98, s64
	v_pk_mul_f32 v[98:99], v[4:5], v[100:101]
	v_lshrrev_b32_e32 v89, 16, v89
	v_bfe_u32 v100, v98, 16, 1
	v_add3_u32 v100, v98, v100, s64
	v_bfe_u32 v98, v99, 16, 1
	v_add3_u32 v99, v99, v98, s64
	v_and_or_b32 v98, v102, s66, v89
	v_lshrrev_b32_e32 v89, 16, v100
	v_pk_mul_f32 v[54:55], v[6:7], v[54:55]
	v_and_or_b32 v99, v99, s66, v89
	v_bfe_u32 v89, v54, 16, 1
	v_lshl_add_u64 v[100:101], v[90:91], 0, s[4:5]
	v_add3_u32 v89, v54, v89, s64
	v_bfe_u32 v54, v55, 16, 1
	global_store_dwordx2 v[100:101], v[98:99], off sc1
	v_add3_u32 v98, v55, v54, s64
	v_pk_mul_f32 v[54:55], v[8:9], v[56:57]
	v_pk_mul_f32 v[50:51], v[14:15], v[50:51]
	v_bfe_u32 v56, v54, 16, 1
	v_add3_u32 v56, v54, v56, s64
	v_bfe_u32 v54, v55, 16, 1
	v_add3_u32 v55, v55, v54, s64
	v_lshrrev_b32_e32 v54, 16, v89
	v_lshrrev_b32_e32 v56, 16, v56
	v_and_or_b32 v54, v98, s66, v54
	v_and_or_b32 v55, v55, s66, v56
	global_store_dwordx2 v[100:101], v[54:55], off offset:512 sc1
	v_pk_mul_f32 v[54:55], v[10:11], v[58:59]
	s_waitcnt vmcnt(13)
	v_pk_mul_f32 v[58:59], v[46:47], v[46:47]
	v_bfe_u32 v56, v54, 16, 1
	v_add3_u32 v89, v54, v56, s64
	v_pk_mul_f32 v[56:57], v[48:49], v[48:49]
	s_waitcnt vmcnt(11)
	v_mul_f32_e32 v54, v39, v39
	v_pk_mov_b32 v[98:99], v[58:59], v[56:57] op_sel:[1,0]
	v_mov_b32_e32 v59, v57
	v_pk_add_f32 v[56:57], v[98:99], v[58:59]
	v_pk_mul_f32 v[58:59], v[44:45], v[44:45]
	v_pk_mul_f32 v[98:99], v[42:43], v[42:43]
	v_pk_add_f32 v[56:57], v[56:57], v[56:57] op_sel:[0,1] op_sel_hi:[1,0]
	v_pk_mov_b32 v[102:103], v[98:99], v[58:59] op_sel:[1,0]
	v_mov_b32_e32 v99, v59
	v_pk_add_f32 v[58:59], v[102:103], v[98:99]
	s_waitcnt vmcnt(10)
	v_mul_f32_e32 v57, v34, v34
	v_pk_add_f32 v[58:59], v[58:59], v[58:59] op_sel:[0,1] op_sel_hi:[1,0]
	v_bfe_u32 v104, v55, 16, 1
	v_mul_f32_e32 v59, v35, v35
	v_pk_add_f32 v[56:57], v[56:57], v[58:59]
	v_pk_fma_f32 v[58:59], v[38:39], v[38:39], v[54:55] op_sel_hi:[1,1,0]
	v_mul_f32_e32 v54, v41, v41
	v_pk_fma_f32 v[98:99], v[40:41], v[40:41], v[54:55] op_sel_hi:[1,1,0]
	v_mul_f32_e32 v59, v36, v36
	v_mul_f32_e32 v99, v37, v37
	v_pk_add_f32 v[58:59], v[58:59], v[98:99]
	s_nop 0
	v_pk_add_f32 v[56:57], v[56:57], v[58:59]
	v_add3_u32 v58, v55, v104, s64
	v_add_f32_e32 v56, v56, v57
	ds_bpermute_b32 v57, v1, v56
	v_pk_mul_f32 v[54:55], v[12:13], v[60:61]
	s_waitcnt lgkmcnt(0)
	v_add_f32_e32 v56, v56, v57
	ds_bpermute_b32 v57, v93, v56
	v_bfe_u32 v59, v54, 16, 1
	v_add3_u32 v59, v54, v59, s64
	v_bfe_u32 v54, v55, 16, 1
	v_add3_u32 v55, v55, v54, s64
	s_waitcnt lgkmcnt(0)
	v_add_f32_e32 v56, v56, v57
	ds_bpermute_b32 v57, v92, v56
	v_lshrrev_b32_e32 v54, 16, v89
	v_and_or_b32 v54, v58, s66, v54
	v_lshrrev_b32_e32 v58, 16, v59
	v_and_or_b32 v55, v55, s66, v58
	global_store_dwordx2 v[100:101], v[54:55], off offset:1024 sc1
	s_waitcnt lgkmcnt(0)
	v_add_f32_e32 v54, v56, v57
	ds_bpermute_b32 v55, v86, v54
	v_bfe_u32 v56, v50, 16, 1
	v_add3_u32 v56, v50, v56, s64
	v_bfe_u32 v50, v51, 16, 1
	v_add3_u32 v57, v51, v50, s64
	s_waitcnt lgkmcnt(0)
	v_add_f32_e32 v54, v54, v55
	ds_bpermute_b32 v55, v82, v54
	v_pk_mul_f32 v[50:51], v[16:17], v[52:53]
	s_waitcnt lgkmcnt(0)
	v_add_f32_e32 v53, v54, v55
	ds_bpermute_b32 v54, v62, v53
	v_bfe_u32 v52, v50, 16, 1
	v_add3_u32 v52, v50, v52, s64
	v_bfe_u32 v50, v51, 16, 1
	v_lshrrev_b32_e32 v60, 16, v52
	s_waitcnt lgkmcnt(0)
	v_add_f32_e32 v52, v53, v54
	v_add3_u32 v51, v51, v50, s64
	v_lshrrev_b32_e32 v50, 16, v56
	v_fmamk_f32 v61, v52, 0x3a800000, v94
	s_waitcnt vmcnt(10)
	v_pk_mul_f32 v[52:53], v[32:33], v[32:33]
	v_pk_mul_f32 v[54:55], v[30:31], v[30:31]
	v_and_or_b32 v50, v57, s66, v50
	v_pk_mov_b32 v[56:57], v[54:55], v[52:53] op_sel:[1,0]
	v_mov_b32_e32 v55, v53
	v_pk_add_f32 v[52:53], v[56:57], v[54:55]
	s_waitcnt vmcnt(9)
	v_pk_mul_f32 v[54:55], v[28:29], v[28:29]
	v_pk_mul_f32 v[56:57], v[26:27], v[26:27]
	v_pk_add_f32 v[52:53], v[52:53], v[52:53] op_sel:[0,1] op_sel_hi:[1,0]
	v_pk_mov_b32 v[58:59], v[56:57], v[54:55] op_sel:[1,0]
	v_mov_b32_e32 v57, v55
	v_pk_add_f32 v[54:55], v[58:59], v[56:57]
	s_waitcnt vmcnt(7)
	v_mul_f32_e32 v53, v18, v18
	v_pk_add_f32 v[54:55], v[54:55], v[54:55] op_sel:[0,1] op_sel_hi:[1,0]
	v_mul_f32_e32 v56, v25, v25
	v_mul_f32_e32 v55, v19, v19
	v_pk_add_f32 v[52:53], v[52:53], v[54:55]
	v_mul_f32_e32 v54, v23, v23
	v_pk_fma_f32 v[54:55], v[22:23], v[22:23], v[54:55] op_sel_hi:[1,1,0]
	v_pk_fma_f32 v[56:57], v[24:25], v[24:25], v[56:57] op_sel_hi:[1,1,0]
	v_mul_f32_e32 v55, v20, v20
	v_mul_f32_e32 v57, v21, v21
	v_pk_add_f32 v[54:55], v[54:55], v[56:57]
	v_mul_f32_e32 v89, 0x4f800000, v61
	v_pk_add_f32 v[52:53], v[52:53], v[54:55]
	v_cmp_gt_f32_e32 vcc, s69, v61
	v_add_f32_e32 v52, v52, v53
	ds_bpermute_b32 v1, v1, v52
	v_cndmask_b32_e32 v53, v61, v89, vcc
	v_sqrt_f32_e32 v54, v53
	v_and_or_b32 v51, v51, s66, v60
	global_store_dwordx2 v[100:101], v[50:51], off offset:1536 sc1
	s_waitcnt lgkmcnt(0)
	v_add_f32_e32 v1, v52, v1
	ds_bpermute_b32 v52, v93, v1
	v_add_u32_e32 v55, -1, v54
	v_fma_f32 v56, -v55, v54, v53
	v_cmp_ge_f32_e64 s[4:5], 0, v56
	v_add_u32_e32 v56, 1, v54
	s_waitcnt lgkmcnt(0)
	v_add_f32_e32 v1, v1, v52
	ds_bpermute_b32 v52, v92, v1
	v_cndmask_b32_e64 v55, v54, v55, s[4:5]
	v_fma_f32 v54, -v56, v54, v53
	v_cmp_lt_f32_e64 s[4:5], 0, v54
	s_waitcnt lgkmcnt(0)
	v_add_f32_e32 v1, v1, v52
	ds_bpermute_b32 v52, v86, v1
	v_cndmask_b32_e64 v54, v55, v56, s[4:5]
	v_mul_f32_e32 v55, 0x37800000, v54
	v_cndmask_b32_e32 v54, v54, v55, vcc
	v_cmp_class_f32_e32 vcc, v53, v95
	s_waitcnt lgkmcnt(0)
	v_add_f32_e32 v1, v1, v52
	ds_bpermute_b32 v52, v82, v1
	v_cndmask_b32_e32 v53, v54, v53, vcc
	v_div_scale_f32 v54, s[4:5], v53, v53, 1.0
	v_rcp_f32_e32 v55, v54
	s_waitcnt lgkmcnt(0)
	v_add_f32_e32 v1, v1, v52
	ds_bpermute_b32 v50, v62, v1
	v_fma_f32 v51, -v54, v55, 1.0
	v_fmac_f32_e32 v55, v51, v55
	v_div_scale_f32 v51, vcc, 1.0, v53, 1.0
	s_waitcnt lgkmcnt(0)
	v_add_f32_e32 v1, v1, v50
	v_fmamk_f32 v1, v1, 0x3a800000, v94
	v_mul_f32_e32 v50, 0x4f800000, v1
	v_cmp_gt_f32_e64 s[4:5], s69, v1
	v_mul_f32_e32 v52, v51, v55
	v_fma_f32 v56, -v54, v52, v51
	v_cndmask_b32_e64 v1, v1, v50, s[4:5]
	v_sqrt_f32_e32 v50, v1
	v_fmac_f32_e32 v52, v56, v55
	v_fma_f32 v51, -v54, v52, v51
	v_div_fmas_f32 v51, v51, v55, v52
	v_add_u32_e32 v56, -1, v50
	v_fma_f32 v57, -v56, v50, v1
	v_cmp_ge_f32_e64 s[6:7], 0, v57
	v_add_u32_e32 v57, 1, v50
	s_nop 0
	v_cndmask_b32_e64 v56, v50, v56, s[6:7]
	v_fma_f32 v50, -v57, v50, v1
	v_cmp_lt_f32_e64 s[6:7], 0, v50
	s_nop 1
	v_cndmask_b32_e64 v50, v56, v57, s[6:7]
	v_mul_f32_e32 v56, 0x37800000, v50
	v_cndmask_b32_e64 v50, v50, v56, s[4:5]
	v_cmp_class_f32_e64 s[4:5], v1, v95
	s_nop 1
	v_cndmask_b32_e64 v1, v50, v1, s[4:5]
	v_div_scale_f32 v50, s[4:5], v1, v1, 1.0
	v_rcp_f32_e32 v56, v50
	s_lshl_b64 s[4:5], s[42:43], 11
	v_fma_f32 v52, -v50, v56, 1.0
	v_fmac_f32_e32 v56, v52, v56
	v_div_scale_f32 v52, vcc, 1.0, v1, 1.0
	v_mul_f32_e32 v54, v52, v56
	v_fma_f32 v55, -v50, v54, v52
	v_fmac_f32_e32 v54, v55, v56
	v_fma_f32 v50, -v50, v54, v52
	v_div_fmas_f32 v52, v50, v56, v54
	v_div_fixup_f32 v50, v51, v53, 1.0
	v_pk_mul_f32 v[46:47], v[46:47], v[50:51] op_sel_hi:[1,0]
	v_pk_mul_f32 v[48:49], v[48:49], v[50:51] op_sel_hi:[1,0]
	v_pk_mul_f32 v[46:47], v[2:3], v[46:47]
	s_nop 0
	v_bfe_u32 v51, v46, 16, 1
	v_add3_u32 v51, v46, v51, s64
	v_bfe_u32 v46, v47, 16, 1
	v_add3_u32 v53, v47, v46, s64
	v_pk_mul_f32 v[46:47], v[4:5], v[48:49]
	v_pk_mul_f32 v[42:43], v[42:43], v[50:51] op_sel_hi:[1,0]
	v_bfe_u32 v48, v46, 16, 1
	v_add3_u32 v49, v46, v48, s64
	v_bfe_u32 v46, v47, 16, 1
	v_add3_u32 v47, v47, v46, s64
	v_div_fixup_f32 v46, v52, v1, 1.0
	v_lshrrev_b32_e32 v1, 16, v51
	v_and_or_b32 v48, v53, s66, v1
	v_lshrrev_b32_e32 v1, 16, v49
	v_pk_mul_f32 v[42:43], v[6:7], v[42:43]
	v_and_or_b32 v49, v47, s66, v1
	v_bfe_u32 v1, v42, 16, 1
	v_pk_mul_f32 v[44:45], v[44:45], v[50:51] op_sel_hi:[1,0]
	v_add3_u32 v1, v42, v1, s64
	v_bfe_u32 v42, v43, 16, 1
	v_pk_mul_f32 v[44:45], v[8:9], v[44:45]
	v_lshrrev_b32_e32 v1, 16, v1
	v_add3_u32 v42, v43, v42, s64
	v_and_or_b32 v42, v42, s66, v1
	v_bfe_u32 v1, v44, 16, 1
	v_add3_u32 v1, v44, v1, s64
	v_bfe_u32 v43, v45, 16, 1
	v_pk_mul_f32 v[38:39], v[38:39], v[50:51] op_sel_hi:[1,0]
	v_lshrrev_b32_e32 v1, 16, v1
	v_add3_u32 v43, v45, v43, s64
	v_pk_mul_f32 v[38:39], v[10:11], v[38:39]
	v_and_or_b32 v43, v43, s66, v1
	v_bfe_u32 v1, v38, 16, 1
	v_pk_mul_f32 v[40:41], v[40:41], v[50:51] op_sel_hi:[1,0]
	v_add3_u32 v1, v38, v1, s64
	v_bfe_u32 v38, v39, 16, 1
	v_pk_mul_f32 v[40:41], v[12:13], v[40:41]
	v_lshrrev_b32_e32 v1, 16, v1
	v_add3_u32 v38, v39, v38, s64
	v_and_or_b32 v38, v38, s66, v1
	v_bfe_u32 v1, v40, 16, 1
	v_add3_u32 v1, v40, v1, s64
	v_bfe_u32 v39, v41, 16, 1
	v_pk_mul_f32 v[34:35], v[34:35], v[50:51] op_sel_hi:[1,0]
	v_lshrrev_b32_e32 v1, 16, v1
	v_add3_u32 v39, v41, v39, s64
	v_pk_mul_f32 v[34:35], v[14:15], v[34:35]
	v_and_or_b32 v39, v39, s66, v1
	v_bfe_u32 v1, v34, 16, 1
	v_pk_mul_f32 v[36:37], v[36:37], v[50:51] op_sel_hi:[1,0]
	v_add3_u32 v1, v34, v1, s64
	v_bfe_u32 v34, v35, 16, 1
	v_pk_mul_f32 v[36:37], v[16:17], v[36:37]
	v_lshrrev_b32_e32 v1, 16, v1
	v_add3_u32 v34, v35, v34, s64
	v_and_or_b32 v34, v34, s66, v1
	v_bfe_u32 v1, v36, 16, 1
	v_add3_u32 v1, v36, v1, s64
	v_bfe_u32 v35, v37, 16, 1
	v_pk_mul_f32 v[30:31], v[30:31], v[46:47] op_sel_hi:[1,0]
	v_lshrrev_b32_e32 v1, 16, v1
	v_add3_u32 v35, v37, v35, s64
	v_pk_mul_f32 v[30:31], v[2:3], v[30:31]
	v_and_or_b32 v35, v35, s66, v1
	v_bfe_u32 v1, v30, 16, 1
	v_pk_mul_f32 v[32:33], v[32:33], v[46:47] op_sel_hi:[1,0]
	v_add3_u32 v1, v30, v1, s64
	v_bfe_u32 v30, v31, 16, 1
	v_pk_mul_f32 v[32:33], v[4:5], v[32:33]
	v_lshrrev_b32_e32 v1, 16, v1
	v_add3_u32 v30, v31, v30, s64
	v_and_or_b32 v30, v30, s66, v1
	v_bfe_u32 v1, v32, 16, 1
	v_add3_u32 v1, v32, v1, s64
	v_bfe_u32 v31, v33, 16, 1
	v_pk_mul_f32 v[26:27], v[26:27], v[46:47] op_sel_hi:[1,0]
	v_lshrrev_b32_e32 v1, 16, v1
	v_add3_u32 v31, v33, v31, s64
	v_pk_mul_f32 v[26:27], v[6:7], v[26:27]
	v_and_or_b32 v31, v31, s66, v1
	v_bfe_u32 v1, v26, 16, 1
	v_pk_mul_f32 v[28:29], v[28:29], v[46:47] op_sel_hi:[1,0]
	v_add3_u32 v1, v26, v1, s64
	v_bfe_u32 v26, v27, 16, 1
	v_pk_mul_f32 v[28:29], v[8:9], v[28:29]
	v_lshrrev_b32_e32 v1, 16, v1
	v_add3_u32 v26, v27, v26, s64
	v_and_or_b32 v26, v26, s66, v1
	v_bfe_u32 v1, v28, 16, 1
	v_add3_u32 v1, v28, v1, s64
	v_bfe_u32 v27, v29, 16, 1
	v_pk_mul_f32 v[22:23], v[22:23], v[46:47] op_sel_hi:[1,0]
	v_lshrrev_b32_e32 v1, 16, v1
	v_add3_u32 v27, v29, v27, s64
	v_pk_mul_f32 v[22:23], v[10:11], v[22:23]
	v_and_or_b32 v27, v27, s66, v1
	v_bfe_u32 v1, v22, 16, 1
	v_pk_mul_f32 v[24:25], v[24:25], v[46:47] op_sel_hi:[1,0]
	v_add3_u32 v1, v22, v1, s64
	v_bfe_u32 v22, v23, 16, 1
	v_pk_mul_f32 v[24:25], v[12:13], v[24:25]
	v_lshrrev_b32_e32 v1, 16, v1
	v_add3_u32 v22, v23, v22, s64
	v_and_or_b32 v22, v22, s66, v1
	v_bfe_u32 v1, v24, 16, 1
	v_add3_u32 v1, v24, v1, s64
	v_bfe_u32 v23, v25, 16, 1
	v_pk_mul_f32 v[18:19], v[18:19], v[46:47] op_sel_hi:[1,0]
	v_lshrrev_b32_e32 v1, 16, v1
	v_add3_u32 v23, v25, v23, s64
	v_pk_mul_f32 v[18:19], v[14:15], v[18:19]
	v_and_or_b32 v23, v23, s66, v1
	v_bfe_u32 v1, v18, 16, 1
	v_pk_mul_f32 v[20:21], v[20:21], v[46:47] op_sel_hi:[1,0]
	v_add3_u32 v1, v18, v1, s64
	v_bfe_u32 v18, v19, 16, 1
	v_pk_mul_f32 v[20:21], v[16:17], v[20:21]
	v_lshrrev_b32_e32 v1, 16, v1
	v_add3_u32 v18, v19, v18, s64
	v_and_or_b32 v18, v18, s66, v1
	v_bfe_u32 v1, v20, 16, 1
	v_add3_u32 v1, v20, v1, s64
	v_bfe_u32 v19, v21, 16, 1
	v_lshl_add_u64 v[52:53], v[90:91], 0, s[4:5]
	s_lshl_b64 s[4:5], s[10:11], 11
	v_lshrrev_b32_e32 v1, 16, v1
	v_add3_u32 v19, v21, v19, s64
	global_store_dwordx2 v[52:53], v[48:49], off sc1
	global_store_dwordx2 v[52:53], v[42:43], off offset:512 sc1
	global_store_dwordx2 v[52:53], v[38:39], off offset:1024 sc1
	global_store_dwordx2 v[52:53], v[34:35], off offset:1536 sc1
	v_lshl_add_u64 v[34:35], v[90:91], 0, s[4:5]
	v_and_or_b32 v19, v19, s66, v1
	v_readfirstlane_b32 s10, v97
	global_store_dwordx2 v[34:35], v[30:31], off sc1
	global_store_dwordx2 v[34:35], v[26:27], off offset:512 sc1
	global_store_dwordx2 v[34:35], v[22:23], off offset:1024 sc1
	global_store_dwordx2 v[34:35], v[18:19], off offset:1536 sc1

.LBB0_720:
	s_add_u32 s44, s10, s14
	s_cmp_gt_i32 s37, 0
	s_cselect_b64 s[6:7], -1, 0
	s_cmp_lt_i32 s37, 1
	s_cbranch_scc1 .LBB0_722
	s_add_u32 s26, s10, s14
	s_addc_u32 s27, s11, s15
	s_add_i32 s28, s44, 0xffff8000
	s_cmp_lt_i32 s44, 0x8000
	s_cselect_b32 s26, s26, s28
	s_cselect_b32 s28, 0, 8
	s_cselect_b32 s27, s27, 0
	s_add_u32 s28, s8, s28
	s_load_dwordx2 s[24:25], s[8:9], 0xc0
	s_addc_u32 s29, s9, 0
	s_load_dwordx2 s[28:29], s[28:29], 0x0
	s_waitcnt vmcnt(0) lgkmcnt(0)
	v_lshl_add_u64 v[18:19], s[24:25], 0, v[84:85]
	s_lshl_b64 s[24:25], s[26:27], 12
	s_add_u32 s24, s28, s24
	s_addc_u32 s25, s29, s25
	v_lshl_add_u64 v[122:123], v[82:83], 4, s[24:25]
	global_load_dwordx2 v[92:93], v[18:19], off offset:-1536
	global_load_dwordx2 v[90:91], v[18:19], off offset:-1024
	global_load_dwordx2 v[88:89], v[18:19], off offset:-512
	global_load_dwordx2 v[86:87], v[18:19], off
	global_load_dwordx4 v[30:33], v[122:123], off nt
	global_load_dwordx4 v[26:29], v[122:123], off offset:1024 nt
	global_load_dwordx4 v[22:25], v[122:123], off offset:2048 nt
	s_nop 0
	global_load_dwordx4 v[18:21], v[122:123], off offset:3072 nt
.LBB0_722:
	s_cmp_gt_i32 s37, 1
	s_cselect_b64 s[28:29], -1, 0
	s_cmp_lt_i32 s37, 2
	s_cbranch_scc1 .LBB0_731
	s_load_dwordx2 s[24:25], s[8:9], 0xc0
	s_add_i32 s26, s44, 1
	s_ashr_i32 s27, s26, 31
	s_lshl_b64 s[30:31], s[26:27], 11
	s_waitcnt lgkmcnt(0)
	s_add_u32 s24, s24, s30
	s_addc_u32 s25, s25, s31
	s_waitcnt vmcnt(0)
	v_lshl_add_u64 v[66:67], v[82:83], 3, s[24:25]
	s_add_i32 s24, s44, 0xffff8001
	s_cmpk_lt_i32 s44, 0x7fff
	s_cselect_b32 s24, s26, s24
	s_cselect_b32 s26, 0, 8
	s_cselect_b32 s25, s27, 0
	s_add_u32 s26, s8, s26
	s_addc_u32 s27, s9, 0
	s_load_dwordx2 s[26:27], s[26:27], 0x0
	s_lshl_b64 s[24:25], s[24:25], 12
	v_lshl_add_u64 v[68:69], v[66:67], 0, s[16:17]
	v_add_co_u32_e32 v66, vcc, s38, v66
	s_waitcnt lgkmcnt(0)
	s_add_u32 s24, s26, s24
	s_addc_u32 s25, s27, s25
	v_addc_co_u32_e32 v67, vcc, 0, v67, vcc
	v_lshl_add_u64 v[122:123], v[82:83], 4, s[24:25]
	global_load_dwordx2 v[116:117], v[66:67], off
	global_load_dwordx2 v[114:115], v[68:69], off offset:512
	global_load_dwordx2 v[112:113], v[68:69], off offset:1024
	global_load_dwordx2 v[110:111], v[68:69], off offset:1536
	global_load_dwordx4 v[78:81], v[122:123], off nt
	global_load_dwordx4 v[74:77], v[122:123], off offset:1024 nt
	global_load_dwordx4 v[70:73], v[122:123], off offset:2048 nt
	s_nop 0
	global_load_dwordx4 v[66:69], v[122:123], off offset:3072 nt
	s_cmp_gt_i32 s37, 2
	s_cselect_b64 s[26:27], -1, 0
	s_cmp_lt_i32 s37, 3
	s_cbranch_scc0 .LBB0_732

.LBB0_725:
	s_load_dwordx2 s[30:31], s[8:9], 0xc0
	s_add_i32 s46, s44, 3
	s_ashr_i32 s47, s46, 31
	s_lshl_b64 s[48:49], s[46:47], 11
	s_waitcnt lgkmcnt(0)
	s_add_u32 s30, s30, s48
	s_addc_u32 s31, s31, s49
	s_waitcnt vmcnt(0)
	v_lshl_add_u64 v[34:35], v[82:83], 3, s[30:31]
	s_add_i32 s30, s44, 0xffff8003
	s_cmpk_lt_i32 s44, 0x7ffd
	s_cselect_b32 s45, 0, 8
	s_cselect_b32 s31, s47, 0
	s_cselect_b32 s30, s46, s30
	s_add_u32 s46, s8, s45
	s_addc_u32 s47, s9, 0
	s_load_dwordx2 s[46:47], s[46:47], 0x0
	s_lshl_b64 s[30:31], s[30:31], 12
	v_lshl_add_u64 v[36:37], v[34:35], 0, s[16:17]
	v_add_co_u32_e32 v34, vcc, s38, v34
	s_waitcnt lgkmcnt(0)
	s_add_u32 s30, s46, s30
	v_addc_co_u32_e32 v35, vcc, 0, v35, vcc
	s_addc_u32 s31, s47, s31
	global_load_dwordx2 v[100:101], v[34:35], off
	global_load_dwordx2 v[98:99], v[36:37], off offset:512
	global_load_dwordx2 v[96:97], v[36:37], off offset:1024
	global_load_dwordx2 v[94:95], v[36:37], off offset:1536
	v_lshl_add_u64 v[34:35], v[82:83], 4, s[30:31]
	global_load_dwordx4 v[46:49], v[34:35], off nt
	global_load_dwordx4 v[42:45], v[34:35], off offset:1024 nt
	global_load_dwordx4 v[38:41], v[34:35], off offset:2048 nt
	s_nop 0
	global_load_dwordx4 v[34:37], v[34:35], off offset:3072 nt
	s_andn2_b64 vcc, exec, s[6:7]
	s_cbranch_vccz .LBB0_734

.LBB0_732:
	s_load_dwordx2 s[24:25], s[8:9], 0xc0
	s_add_i32 s30, s44, 2
	s_ashr_i32 s31, s30, 31
	s_lshl_b64 s[46:47], s[30:31], 11
	s_waitcnt lgkmcnt(0)
	s_add_u32 s24, s24, s46
	s_addc_u32 s25, s25, s47
	s_waitcnt vmcnt(0)
	v_lshl_add_u64 v[50:51], v[82:83], 3, s[24:25]
	s_add_i32 s24, s44, 0xffff8002
	s_cmpk_lt_i32 s44, 0x7ffe
	s_cselect_b32 s24, s30, s24
	s_cselect_b32 s30, 0, 8
	s_cselect_b32 s25, s31, 0
	s_add_u32 s30, s8, s30
	s_addc_u32 s31, s9, 0
	s_load_dwordx2 s[30:31], s[30:31], 0x0
	s_lshl_b64 s[24:25], s[24:25], 12
	v_lshl_add_u64 v[52:53], v[50:51], 0, s[16:17]
	v_add_co_u32_e32 v50, vcc, s38, v50
	s_waitcnt lgkmcnt(0)
	s_add_u32 s24, s30, s24
	s_addc_u32 s25, s31, s25
	v_addc_co_u32_e32 v51, vcc, 0, v51, vcc
	v_lshl_add_u64 v[122:123], v[82:83], 4, s[24:25]
	global_load_dwordx2 v[108:109], v[50:51], off
	global_load_dwordx2 v[106:107], v[52:53], off offset:512
	global_load_dwordx2 v[104:105], v[52:53], off offset:1024
	global_load_dwordx2 v[102:103], v[52:53], off offset:1536
	global_load_dwordx4 v[62:65], v[122:123], off nt
	global_load_dwordx4 v[58:61], v[122:123], off offset:1024 nt
	global_load_dwordx4 v[54:57], v[122:123], off offset:2048 nt
	s_nop 0
	global_load_dwordx4 v[50:53], v[122:123], off offset:3072 nt
	s_cmp_gt_i32 s37, 3
	s_cselect_b64 s[24:25], -1, 0
	s_cmp_lt_i32 s37, 4
	s_cbranch_scc0 .LBB0_725
